# v30: v28 + epilogue row-sum shuffles (xor 16 / xor 32) as v_permlane16/32_swap instead of ds_bpermute LDS round trips in kv-up, out-proj and xattn-out epilogues (20 chains)
# baseline (speedup 1.0000x reference)
;     __device__ __forceinline__ void with_lds(const f32x4 (&acc)[2][2][4][2], const Unit& u, int wr, int wc, int fr, int fq, PG8_LAS unsigned char* lds) const {
;     ...
;             for (int m = 0; m < 4; ++m) { const f32x4 a = acc[ai][0][m][0], b = acc[ai][0][m][1];
;                 float s = (a[0] * a[0] + a[1] * a[1]) + (a[2] * a[2] + a[3] * a[3]) + (b[0] * b[0] + b[1] * b[1]) + (b[2] * b[2] + b[3] * b[3]);
;                 s += __shfl_xor(s, 16); s += __shfl_xor(s, 32);
;                 if (fq == 0) part[(ai * HALF + rb + m * 16) * 4 + wc] = s; }
.LBB0_1054:
	v_and_b32_e32 v84, 64, v229
	v_xor_b32_e32 v1, 16, v229
	v_add_u32_e32 v85, 64, v84
	v_cmp_lt_i32_e32 vcc, v1, v85
	v_mul_f32_e32 v86, v139, v139
	v_fmac_f32_e32 v86, v138, v138
	v_cndmask_b32_e32 v1, v229, v1, vcc
	v_lshlrev_b32_e32 v84, 2, v1
	v_mul_f32_e32 v1, v137, v137
	v_fmac_f32_e32 v1, v136, v136
	v_add_f32_e32 v1, v1, v86
	v_mul_f32_e32 v86, v133, v133
	v_fmac_f32_e32 v86, v132, v132
	v_add_f32_e32 v1, v86, v1
	v_mul_f32_e32 v86, v135, v135
	v_fmac_f32_e32 v86, v134, v134
	v_add_f32_e32 v1, v86, v1
	v_mov_b32_e32 v86, v1
	s_nop 1
	v_permlane16_swap_b32_e32 v86, v1
	v_xor_b32_e32 v87, 32, v229
	v_cmp_lt_i32_e32 vcc, v87, v85
	s_waitcnt lgkmcnt(0)
	v_add_f32_e32 v86, v1, v86
	v_cndmask_b32_e32 v85, v229, v87, vcc
	v_lshlrev_b32_e32 v85, 2, v85
	v_mov_b32_e32 v87, v86
	s_nop 1
	v_permlane32_swap_b32_e32 v87, v86
	s_and_saveexec_b64 s[0:1], s[38:39]
	s_cbranch_execz .LBB0_1056
	s_waitcnt lgkmcnt(0)
	v_add_f32_e32 v1, v86, v87
	ds_write_b32 v159, v1
.LBB0_1056:
	s_or_b64 exec, exec, s[0:1]
	v_mul_f32_e32 v1, v129, v129
	v_mul_f32_e32 v86, v131, v131
	v_fmac_f32_e32 v1, v128, v128
	v_fmac_f32_e32 v86, v130, v130
	v_add_f32_e32 v1, v1, v86
	v_mul_f32_e32 v86, v121, v121
	v_fmac_f32_e32 v86, v120, v120
	v_add_f32_e32 v1, v86, v1
	v_mul_f32_e32 v86, v123, v123
	v_fmac_f32_e32 v86, v122, v122
	v_add_f32_e32 v1, v86, v1
	v_mov_b32_e32 v86, v1
	s_nop 1
	v_permlane16_swap_b32_e32 v86, v1
	s_waitcnt lgkmcnt(0)
	v_add_f32_e32 v86, v1, v86
	v_mov_b32_e32 v87, v86
	s_nop 1
	v_permlane32_swap_b32_e32 v87, v86
	s_and_saveexec_b64 s[0:1], s[38:39]
	s_cbranch_execz .LBB0_1058
	s_waitcnt lgkmcnt(0)
	v_add_f32_e32 v1, v86, v87
	ds_write_b32 v159, v1 offset:256
.LBB0_1058:
	s_or_b64 exec, exec, s[0:1]
	v_mul_f32_e32 v1, v105, v105
	v_mul_f32_e32 v86, v107, v107
	v_fmac_f32_e32 v1, v104, v104
	v_fmac_f32_e32 v86, v106, v106
	v_add_f32_e32 v1, v1, v86
	v_mul_f32_e32 v86, v101, v101
	v_fmac_f32_e32 v86, v100, v100
	v_add_f32_e32 v1, v86, v1
	v_mul_f32_e32 v86, v103, v103
	v_fmac_f32_e32 v86, v102, v102
	v_add_f32_e32 v1, v86, v1
	v_mov_b32_e32 v86, v1
	s_nop 1
	v_permlane16_swap_b32_e32 v86, v1
	s_waitcnt lgkmcnt(0)
	v_add_f32_e32 v86, v1, v86
	v_mov_b32_e32 v87, v86
	s_nop 1
	v_permlane32_swap_b32_e32 v87, v86
	s_and_saveexec_b64 s[0:1], s[38:39]
	s_cbranch_execz .LBB0_1060
	s_waitcnt lgkmcnt(0)
	v_add_f32_e32 v1, v86, v87
	ds_write_b32 v159, v1 offset:512
.LBB0_1060:
	s_or_b64 exec, exec, s[0:1]
	v_mul_f32_e32 v1, v81, v81
	v_mul_f32_e32 v86, v83, v83
	v_fmac_f32_e32 v1, v80, v80
	v_fmac_f32_e32 v86, v82, v82
	v_add_f32_e32 v1, v1, v86
	v_mul_f32_e32 v86, v77, v77
	v_fmac_f32_e32 v86, v76, v76
	v_add_f32_e32 v1, v86, v1
	v_mul_f32_e32 v86, v79, v79
	v_fmac_f32_e32 v86, v78, v78
	v_add_f32_e32 v1, v86, v1
	v_mov_b32_e32 v86, v1
	s_nop 1
	v_permlane16_swap_b32_e32 v86, v1
	s_waitcnt lgkmcnt(0)
	v_add_f32_e32 v86, v1, v86
	v_mov_b32_e32 v87, v86
	s_nop 1
	v_permlane32_swap_b32_e32 v87, v86
	s_and_saveexec_b64 s[0:1], s[38:39]
	s_cbranch_execz .LBB0_1062
	s_waitcnt lgkmcnt(0)
	v_add_f32_e32 v1, v86, v87
	ds_write_b32 v159, v1 offset:768
.LBB0_1062:
	s_or_b64 exec, exec, s[0:1]
	v_mul_f32_e32 v1, v65, v65
	v_mul_f32_e32 v86, v67, v67
	v_fmac_f32_e32 v1, v64, v64
	v_fmac_f32_e32 v86, v66, v66
	v_add_f32_e32 v1, v1, v86
	v_mul_f32_e32 v86, v61, v61
	v_fmac_f32_e32 v86, v60, v60
	v_add_f32_e32 v1, v86, v1
	v_mul_f32_e32 v86, v63, v63
	v_fmac_f32_e32 v86, v62, v62
	v_add_f32_e32 v1, v86, v1
	v_mov_b32_e32 v86, v1
	s_nop 1
	v_permlane16_swap_b32_e32 v86, v1
	s_waitcnt lgkmcnt(0)
	v_add_f32_e32 v86, v1, v86
	v_mov_b32_e32 v87, v86
	s_nop 1
	v_permlane32_swap_b32_e32 v87, v86
	s_and_saveexec_b64 s[0:1], s[38:39]
	s_cbranch_execz .LBB0_1064
	s_waitcnt lgkmcnt(0)
	v_add_f32_e32 v1, v86, v87
	ds_write_b32 v159, v1 offset:2048
.LBB0_1064:
	s_or_b64 exec, exec, s[0:1]
	v_mul_f32_e32 v1, v49, v49
	v_mul_f32_e32 v86, v51, v51
	v_fmac_f32_e32 v1, v48, v48
	v_fmac_f32_e32 v86, v50, v50
	v_add_f32_e32 v1, v1, v86
	v_mul_f32_e32 v86, v45, v45
	v_fmac_f32_e32 v86, v44, v44
	v_add_f32_e32 v1, v86, v1
	v_mul_f32_e32 v86, v47, v47
	v_fmac_f32_e32 v86, v46, v46
	v_add_f32_e32 v1, v86, v1
	v_mov_b32_e32 v86, v1
	s_nop 1
	v_permlane16_swap_b32_e32 v86, v1
	s_waitcnt lgkmcnt(0)
	v_add_f32_e32 v86, v1, v86
	v_mov_b32_e32 v87, v86
	s_nop 1
	v_permlane32_swap_b32_e32 v87, v86
	s_and_saveexec_b64 s[0:1], s[38:39]
	s_cbranch_execz .LBB0_1066
	s_waitcnt lgkmcnt(0)
	v_add_f32_e32 v1, v86, v87
	ds_write_b32 v159, v1 offset:2304
.LBB0_1066:
	s_or_b64 exec, exec, s[0:1]
	v_mul_f32_e32 v1, v33, v33
	v_mul_f32_e32 v86, v35, v35
	v_fmac_f32_e32 v1, v32, v32
	v_fmac_f32_e32 v86, v34, v34
	v_add_f32_e32 v1, v1, v86
	v_mul_f32_e32 v86, v29, v29
	v_fmac_f32_e32 v86, v28, v28
	v_add_f32_e32 v1, v86, v1
	v_mul_f32_e32 v86, v31, v31
	v_fmac_f32_e32 v86, v30, v30
	v_add_f32_e32 v1, v86, v1
	v_mov_b32_e32 v86, v1
	s_nop 1
	v_permlane16_swap_b32_e32 v86, v1
	s_waitcnt lgkmcnt(0)
	v_add_f32_e32 v86, v1, v86
	v_mov_b32_e32 v87, v86
	s_nop 1
	v_permlane32_swap_b32_e32 v87, v86
	s_and_saveexec_b64 s[0:1], s[38:39]
	s_cbranch_execz .LBB0_1068
	s_waitcnt lgkmcnt(0)
	v_add_f32_e32 v1, v86, v87
	ds_write_b32 v159, v1 offset:2560
.LBB0_1068:
	s_or_b64 exec, exec, s[0:1]
	v_mul_f32_e32 v1, v17, v17
	v_mul_f32_e32 v86, v19, v19
	v_fmac_f32_e32 v1, v16, v16
	v_fmac_f32_e32 v86, v18, v18
	v_add_f32_e32 v1, v1, v86
	v_mul_f32_e32 v86, v13, v13
	v_fmac_f32_e32 v86, v12, v12
	v_add_f32_e32 v1, v86, v1
	v_mul_f32_e32 v86, v15, v15
	v_fmac_f32_e32 v86, v14, v14
	v_add_f32_e32 v1, v86, v1
	v_mov_b32_e32 v84, v1
	s_nop 1
	v_permlane16_swap_b32_e32 v84, v1
	s_waitcnt lgkmcnt(0)
	v_add_f32_e32 v84, v1, v84
	v_mov_b32_e32 v85, v84
	s_nop 1
	v_permlane32_swap_b32_e32 v85, v84
	s_and_saveexec_b64 s[0:1], s[38:39]
	s_cbranch_execz .LBB0_1070
	s_waitcnt lgkmcnt(0)
	v_add_f32_e32 v1, v84, v85
	ds_write_b32 v159, v1 offset:2816

; __device__ __forceinline__ unsigned pkbf(float lo, float hi) { f32x2v v = {lo, hi}; bf16x2v b = __builtin_convertvector(v, bf16x2v); return __builtin_bit_cast(unsigned, b); }
;     __device__ __forceinline__ void operator()(const f32x4 (&acc)[2][2][4][2], const Unit& u, int wr, int wc, int fr, int fq) const {
;     ...
;                 const int r = row0 + ai * HALF + m * 16;
;                 bf16_t* xp = XB + (size_t)r * 4096 + col0; float sq = 0.f;
;                 const u32x4 o0 = *(const u32x4*)xp, o1 = *(const u32x4*)(xp + HALF);
; #pragma unroll
;                 for (int bj = 0; bj < 2; ++bj) {
;                     const u32x4 o = bj ? o1 : o0;
;                     f32x4 a = {__uint_as_float(o.x << 16), __uint_as_float(o.x & 0xffff0000u), __uint_as_float(o.y << 16), __uint_as_float(o.y & 0xffff0000u)};
;                     f32x4 b = {__uint_as_float(o.z << 16), __uint_as_float(o.z & 0xffff0000u), __uint_as_float(o.w << 16), __uint_as_float(o.w & 0xffff0000u)};
;                     a += acc[ai][bj][m][0]; b += acc[ai][bj][m][1];
;                     if (Y) { float* yp = Y + (size_t)r * 4096 + col0 + bj * HALF; *(f32x4*)yp = a; *(f32x4*)(yp + 4) = b; }
;                     else {
;                         sq += (a[0] * a[0] + a[1] * a[1]) + (a[2] * a[2] + a[3] * a[3]) + (b[0] * b[0] + b[1] * b[1]) + (b[2] * b[2] + b[3] * b[3]);
;                         u32x4 w; w.x = pkbf(a[0], a[1]); w.y = pkbf(a[2], a[3]); w.z = pkbf(b[0], b[1]); w.w = pkbf(b[2], b[3]);
;                         *(u32x4*)(xp + bj * HALF) = w; } }
;                 if (!Y) { sq += __shfl_xor(sq, 16); sq += __shfl_xor(sq, 32); if (fq == 0) unsafeAtomicAdd(ssq + r, sq); }
.LBB0_1629:
	s_or_b64 exec, exec, s[0:1]
	v_or_b32_e32 v116, 16, v144
	s_waitcnt lgkmcnt(0)
	v_ashrrev_i32_e32 v117, 31, v116
	v_lshlrev_b64 v[118:119], 13, v[116:117]
	v_lshl_add_u64 v[118:119], s[36:37], 0, v[118:119]
	v_lshl_add_u64 v[118:119], v[142:143], 1, v[118:119]
	s_waitcnt vmcnt(11)
	v_lshlrev_b32_e32 v130, 16, v164
	v_and_b32_e32 v131, 0xffff0000, v164
	v_lshlrev_b32_e32 v122, 16, v165
	v_and_b32_e32 v123, 0xffff0000, v165
	v_lshlrev_b32_e32 v150, 16, v166
	v_and_b32_e32 v151, 0xffff0000, v166
	v_lshlrev_b32_e32 v124, 16, v167
	v_and_b32_e32 v125, 0xffff0000, v167
	v_pk_add_f32 v[114:115], v[114:115], v[122:123]
	v_pk_add_f32 v[112:113], v[112:113], v[130:131]
	v_pk_add_f32 v[122:123], v[110:111], v[124:125]
	v_pk_add_f32 v[110:111], v[108:109], v[150:151]
	v_mul_f32_e32 v1, v113, v113
	v_mul_f32_e32 v108, v115, v115
	v_fmac_f32_e32 v1, v112, v112
	v_fmac_f32_e32 v108, v114, v114
	v_add_f32_e32 v1, v1, v108
	v_mul_f32_e32 v108, v111, v111
	v_fmac_f32_e32 v108, v110, v110
	v_add_f32_e32 v1, v108, v1
	v_mul_f32_e32 v108, v123, v123
	v_fmac_f32_e32 v108, v122, v122
	v_add_f32_e32 v1, v108, v1
	v_cvt_pk_bf16_f32 v108, v112, v113
	v_cvt_pk_bf16_f32 v109, v114, v115
	v_cvt_pk_bf16_f32 v110, v110, v111
	v_cvt_pk_bf16_f32 v111, v122, v123
	global_store_dwordx4 v[118:119], v[108:111], off
	v_lshlrev_b32_e32 v112, 16, v170
	v_and_b32_e32 v113, 0xffff0000, v170
	v_lshlrev_b32_e32 v108, 16, v168
	v_and_b32_e32 v109, 0xffff0000, v168
	v_lshlrev_b32_e32 v110, 16, v169
	v_and_b32_e32 v111, 0xffff0000, v169
	v_lshlrev_b32_e32 v114, 16, v171
	v_and_b32_e32 v115, 0xffff0000, v171
	v_pk_add_f32 v[106:107], v[106:107], v[110:111]
	v_pk_add_f32 v[104:105], v[104:105], v[108:109]
	v_pk_add_f32 v[108:109], v[102:103], v[114:115]
	v_pk_add_f32 v[102:103], v[100:101], v[112:113]
	v_mul_f32_e32 v100, v105, v105
	v_mul_f32_e32 v101, v107, v107
	v_fmac_f32_e32 v100, v104, v104
	v_fmac_f32_e32 v101, v106, v106
	v_add_f32_e32 v100, v100, v101
	v_mul_f32_e32 v101, v103, v103
	v_fmac_f32_e32 v101, v102, v102
	v_add_f32_e32 v100, v101, v100
	v_mul_f32_e32 v101, v109, v109
	v_fmac_f32_e32 v101, v108, v108
	v_add_f32_e32 v100, v101, v100
	v_add_f32_e32 v1, v1, v100
	v_cvt_pk_bf16_f32 v100, v104, v105
	v_cvt_pk_bf16_f32 v101, v106, v107
	v_cvt_pk_bf16_f32 v102, v102, v103
	v_cvt_pk_bf16_f32 v103, v108, v109
	global_store_dwordx4 v[118:119], v[100:103], off offset:256
	s_nop 1
	v_mov_b32_e32 v100, v1
	s_nop 1
	v_permlane16_swap_b32_e32 v100, v1
	s_waitcnt lgkmcnt(0)
	v_add_f32_e32 v100, v1, v100
	v_mov_b32_e32 v101, v100
	s_nop 1
	v_permlane32_swap_b32_e32 v101, v100
	s_and_saveexec_b64 s[0:1], s[38:39]
	s_cbranch_execz .LBB0_1631
	v_lshl_add_u64 v[102:103], v[116:117], 2, s[42:43]
	s_waitcnt lgkmcnt(0)
	v_add_f32_e32 v1, v100, v101
	global_atomic_add_f32 v[102:103], v1, off
.LBB0_1631:
	s_or_b64 exec, exec, s[0:1]
	s_mov_b64 s[100:101], 0x140000
	v_lshl_add_u64 v[204:205], v[158:159], 0, s[100:101]
	global_load_dwordx4 v[164:167], v[204:205], off
	global_load_dwordx4 v[168:171], v[204:205], off offset:256
	v_or_b32_e32 v100, 32, v144
	s_waitcnt lgkmcnt(0)
	v_ashrrev_i32_e32 v101, 31, v100
	v_lshlrev_b64 v[102:103], 13, v[100:101]
	v_lshl_add_u64 v[102:103], s[36:37], 0, v[102:103]
	v_lshl_add_u64 v[102:103], v[142:143], 1, v[102:103]
	s_waitcnt vmcnt(14)
	v_lshlrev_b32_e32 v112, 16, v172
	v_and_b32_e32 v113, 0xffff0000, v172
	v_lshlrev_b32_e32 v104, 16, v173
	v_and_b32_e32 v105, 0xffff0000, v173
	v_lshlrev_b32_e32 v114, 16, v174
	v_and_b32_e32 v115, 0xffff0000, v174
	v_lshlrev_b32_e32 v106, 16, v175
	v_and_b32_e32 v107, 0xffff0000, v175
	v_pk_add_f32 v[98:99], v[98:99], v[104:105]
	v_pk_add_f32 v[96:97], v[96:97], v[112:113]
	v_pk_add_f32 v[104:105], v[94:95], v[106:107]
	v_pk_add_f32 v[94:95], v[92:93], v[114:115]
	v_mul_f32_e32 v1, v97, v97
	v_mul_f32_e32 v92, v99, v99
	v_fmac_f32_e32 v1, v96, v96
	v_fmac_f32_e32 v92, v98, v98
	v_add_f32_e32 v1, v1, v92
	v_mul_f32_e32 v92, v95, v95
	v_fmac_f32_e32 v92, v94, v94
	v_add_f32_e32 v1, v92, v1
	v_mul_f32_e32 v92, v105, v105
	v_fmac_f32_e32 v92, v104, v104
	v_add_f32_e32 v1, v92, v1
	v_cvt_pk_bf16_f32 v92, v96, v97
	v_cvt_pk_bf16_f32 v93, v98, v99
	v_cvt_pk_bf16_f32 v94, v94, v95
	v_cvt_pk_bf16_f32 v95, v104, v105
	global_store_dwordx4 v[102:103], v[92:95], off
	v_lshlrev_b32_e32 v96, 16, v178
	v_and_b32_e32 v97, 0xffff0000, v178
	v_lshlrev_b32_e32 v92, 16, v176
	v_and_b32_e32 v93, 0xffff0000, v176
	v_lshlrev_b32_e32 v94, 16, v177
	v_and_b32_e32 v95, 0xffff0000, v177
	v_lshlrev_b32_e32 v98, 16, v179
	v_and_b32_e32 v99, 0xffff0000, v179
	v_pk_add_f32 v[90:91], v[90:91], v[94:95]
	v_pk_add_f32 v[88:89], v[88:89], v[92:93]
	v_pk_add_f32 v[92:93], v[86:87], v[98:99]
	v_pk_add_f32 v[86:87], v[84:85], v[96:97]
	v_mul_f32_e32 v84, v89, v89
	v_mul_f32_e32 v85, v91, v91
	v_fmac_f32_e32 v84, v88, v88
	v_fmac_f32_e32 v85, v90, v90
	v_add_f32_e32 v84, v84, v85
	v_mul_f32_e32 v85, v87, v87
	v_fmac_f32_e32 v85, v86, v86
	v_add_f32_e32 v84, v85, v84
	v_mul_f32_e32 v85, v93, v93
	v_fmac_f32_e32 v85, v92, v92
	v_add_f32_e32 v84, v85, v84
	v_add_f32_e32 v1, v1, v84
	v_cvt_pk_bf16_f32 v84, v88, v89
	v_cvt_pk_bf16_f32 v85, v90, v91
	v_cvt_pk_bf16_f32 v86, v86, v87
	v_cvt_pk_bf16_f32 v87, v92, v93
	global_store_dwordx4 v[102:103], v[84:87], off offset:256
	s_nop 1
	v_mov_b32_e32 v84, v1
	s_nop 1
	v_permlane16_swap_b32_e32 v84, v1
	s_waitcnt lgkmcnt(0)
	v_add_f32_e32 v84, v1, v84
	v_mov_b32_e32 v85, v84
	s_nop 1
	v_permlane32_swap_b32_e32 v85, v84
	s_and_saveexec_b64 s[0:1], s[38:39]
	s_cbranch_execz .LBB0_1633
	v_lshl_add_u64 v[86:87], v[100:101], 2, s[42:43]
	s_waitcnt lgkmcnt(0)
	v_add_f32_e32 v1, v84, v85
	global_atomic_add_f32 v[86:87], v1, off
; __device__ __forceinline__ unsigned pkbf(float lo, float hi) { f32x2v v = {lo, hi}; bf16x2v b = __builtin_convertvector(v, bf16x2v); return __builtin_bit_cast(unsigned, b); }
;     __device__ __forceinline__ void operator()(const f32x4 (&acc)[2][2][4][2], const Unit& u, int wr, int wc, int fr, int fq) const {
;     ...
;                 const int r = row0 + ai * HALF + m * 16;
;                 bf16_t* xp = XB + (size_t)r * 4096 + col0; float sq = 0.f;
;                 const u32x4 o0 = *(const u32x4*)xp, o1 = *(const u32x4*)(xp + HALF);
; #pragma unroll
;                 for (int bj = 0; bj < 2; ++bj) {
;                     const u32x4 o = bj ? o1 : o0;
;                     f32x4 a = {__uint_as_float(o.x << 16), __uint_as_float(o.x & 0xffff0000u), __uint_as_float(o.y << 16), __uint_as_float(o.y & 0xffff0000u)};
;                     f32x4 b = {__uint_as_float(o.z << 16), __uint_as_float(o.z & 0xffff0000u), __uint_as_float(o.w << 16), __uint_as_float(o.w & 0xffff0000u)};
;                     a += acc[ai][bj][m][0]; b += acc[ai][bj][m][1];
;                     if (Y) { float* yp = Y + (size_t)r * 4096 + col0 + bj * HALF; *(f32x4*)yp = a; *(f32x4*)(yp + 4) = b; }
;                     else {
;                         sq += (a[0] * a[0] + a[1] * a[1]) + (a[2] * a[2] + a[3] * a[3]) + (b[0] * b[0] + b[1] * b[1]) + (b[2] * b[2] + b[3] * b[3]);
;                         u32x4 w; w.x = pkbf(a[0], a[1]); w.y = pkbf(a[2], a[3]); w.z = pkbf(b[0], b[1]); w.w = pkbf(b[2], b[3]);
;                         *(u32x4*)(xp + bj * HALF) = w; } }
;                 if (!Y) { sq += __shfl_xor(sq, 16); sq += __shfl_xor(sq, 32); if (fq == 0) unsafeAtomicAdd(ssq + r, sq); }
.LBB0_1633:
	s_or_b64 exec, exec, s[0:1]
	s_mov_b64 s[100:101], 0x160000
	v_lshl_add_u64 v[204:205], v[158:159], 0, s[100:101]
	global_load_dwordx4 v[172:175], v[204:205], off
	global_load_dwordx4 v[176:179], v[204:205], off offset:256
	v_or_b32_e32 v84, 48, v144
	s_waitcnt lgkmcnt(0)
	v_ashrrev_i32_e32 v85, 31, v84
	v_lshlrev_b64 v[86:87], 13, v[84:85]
	v_lshl_add_u64 v[86:87], s[36:37], 0, v[86:87]
	v_lshl_add_u64 v[86:87], v[142:143], 1, v[86:87]
	s_waitcnt vmcnt(17)
	v_lshlrev_b32_e32 v96, 16, v180
	v_and_b32_e32 v97, 0xffff0000, v180
	v_lshlrev_b32_e32 v88, 16, v181
	v_and_b32_e32 v89, 0xffff0000, v181
	v_lshlrev_b32_e32 v98, 16, v182
	v_and_b32_e32 v99, 0xffff0000, v182
	v_lshlrev_b32_e32 v90, 16, v183
	v_and_b32_e32 v91, 0xffff0000, v183
	v_pk_add_f32 v[82:83], v[82:83], v[88:89]
	v_pk_add_f32 v[80:81], v[80:81], v[96:97]
	v_pk_add_f32 v[88:89], v[78:79], v[90:91]
	v_pk_add_f32 v[78:79], v[76:77], v[98:99]
	v_mul_f32_e32 v1, v81, v81
	v_mul_f32_e32 v76, v83, v83
	v_fmac_f32_e32 v1, v80, v80
	v_fmac_f32_e32 v76, v82, v82
	v_add_f32_e32 v1, v1, v76
	v_mul_f32_e32 v76, v79, v79
	v_fmac_f32_e32 v76, v78, v78
	v_add_f32_e32 v1, v76, v1
	v_mul_f32_e32 v76, v89, v89
	v_fmac_f32_e32 v76, v88, v88
	v_add_f32_e32 v1, v76, v1
	v_cvt_pk_bf16_f32 v76, v80, v81
	v_cvt_pk_bf16_f32 v77, v82, v83
	v_cvt_pk_bf16_f32 v78, v78, v79
	v_cvt_pk_bf16_f32 v79, v88, v89
	global_store_dwordx4 v[86:87], v[76:79], off
	v_lshlrev_b32_e32 v80, 16, v186
	v_and_b32_e32 v81, 0xffff0000, v186
	v_lshlrev_b32_e32 v76, 16, v184
	v_and_b32_e32 v77, 0xffff0000, v184
	v_lshlrev_b32_e32 v78, 16, v185
	v_and_b32_e32 v79, 0xffff0000, v185
	v_lshlrev_b32_e32 v82, 16, v187
	v_and_b32_e32 v83, 0xffff0000, v187
	v_pk_add_f32 v[74:75], v[74:75], v[78:79]
	v_pk_add_f32 v[72:73], v[72:73], v[76:77]
	v_pk_add_f32 v[76:77], v[70:71], v[82:83]
	v_pk_add_f32 v[70:71], v[68:69], v[80:81]
	v_mul_f32_e32 v68, v73, v73
	v_mul_f32_e32 v69, v75, v75
	v_fmac_f32_e32 v68, v72, v72
	v_fmac_f32_e32 v69, v74, v74
	v_add_f32_e32 v68, v68, v69
	v_mul_f32_e32 v69, v71, v71
	v_fmac_f32_e32 v69, v70, v70
	v_add_f32_e32 v68, v69, v68
	v_mul_f32_e32 v69, v77, v77
	v_fmac_f32_e32 v69, v76, v76
	v_add_f32_e32 v68, v69, v68
	v_add_f32_e32 v1, v1, v68
	v_cvt_pk_bf16_f32 v68, v72, v73
	v_cvt_pk_bf16_f32 v69, v74, v75
	v_cvt_pk_bf16_f32 v70, v70, v71
	v_cvt_pk_bf16_f32 v71, v76, v77
	global_store_dwordx4 v[86:87], v[68:71], off offset:256
	s_nop 1
	v_mov_b32_e32 v68, v1
	s_nop 1
	v_permlane16_swap_b32_e32 v68, v1
	s_waitcnt lgkmcnt(0)
	v_add_f32_e32 v68, v1, v68
	v_mov_b32_e32 v69, v68
	s_nop 1
	v_permlane32_swap_b32_e32 v69, v68
	s_and_saveexec_b64 s[0:1], s[38:39]
	s_cbranch_execz .LBB0_1635
	v_lshl_add_u64 v[70:71], v[84:85], 2, s[42:43]
	s_waitcnt lgkmcnt(0)
	v_add_f32_e32 v1, v68, v69
	global_atomic_add_f32 v[70:71], v1, off
.LBB0_1635:
	s_or_b64 exec, exec, s[0:1]
	v_add_u32_e32 v68, 0x80, v144
	s_waitcnt lgkmcnt(0)
	v_ashrrev_i32_e32 v69, 31, v68
	v_lshlrev_b64 v[70:71], 13, v[68:69]
	v_lshl_add_u64 v[70:71], s[36:37], 0, v[70:71]
	v_lshl_add_u64 v[70:71], v[142:143], 1, v[70:71]
	s_waitcnt vmcnt(18)
	v_lshlrev_b32_e32 v80, 16, v188
	v_and_b32_e32 v81, 0xffff0000, v188
	v_lshlrev_b32_e32 v72, 16, v189
	v_and_b32_e32 v73, 0xffff0000, v189
	v_lshlrev_b32_e32 v82, 16, v190
	v_and_b32_e32 v83, 0xffff0000, v190
	v_lshlrev_b32_e32 v74, 16, v191
	v_and_b32_e32 v75, 0xffff0000, v191
	v_pk_add_f32 v[66:67], v[66:67], v[72:73]
	v_pk_add_f32 v[64:65], v[64:65], v[80:81]
	v_pk_add_f32 v[72:73], v[62:63], v[74:75]
	v_pk_add_f32 v[62:63], v[60:61], v[82:83]
	v_mul_f32_e32 v1, v65, v65
	v_mul_f32_e32 v60, v67, v67
	v_fmac_f32_e32 v1, v64, v64
	v_fmac_f32_e32 v60, v66, v66
	v_add_f32_e32 v1, v1, v60
	v_mul_f32_e32 v60, v63, v63
	v_fmac_f32_e32 v60, v62, v62
	v_add_f32_e32 v1, v60, v1
	v_mul_f32_e32 v60, v73, v73
	v_fmac_f32_e32 v60, v72, v72
	v_add_f32_e32 v1, v60, v1
	v_cvt_pk_bf16_f32 v60, v64, v65
	v_cvt_pk_bf16_f32 v61, v66, v67
	v_cvt_pk_bf16_f32 v62, v62, v63
	v_cvt_pk_bf16_f32 v63, v72, v73
	global_store_dwordx4 v[70:71], v[60:63], off
	v_lshlrev_b32_e32 v64, 16, v194
	v_and_b32_e32 v65, 0xffff0000, v194
	v_lshlrev_b32_e32 v60, 16, v192
	v_and_b32_e32 v61, 0xffff0000, v192
	v_lshlrev_b32_e32 v62, 16, v193
	v_and_b32_e32 v63, 0xffff0000, v193
	v_lshlrev_b32_e32 v66, 16, v195
	v_and_b32_e32 v67, 0xffff0000, v195
	v_pk_add_f32 v[58:59], v[58:59], v[62:63]
	v_pk_add_f32 v[56:57], v[56:57], v[60:61]
	v_pk_add_f32 v[60:61], v[54:55], v[66:67]
	v_pk_add_f32 v[54:55], v[52:53], v[64:65]
	v_mul_f32_e32 v52, v57, v57
	v_mul_f32_e32 v53, v59, v59
	v_fmac_f32_e32 v52, v56, v56
	v_fmac_f32_e32 v53, v58, v58
	v_add_f32_e32 v52, v52, v53
	v_mul_f32_e32 v53, v55, v55
	v_fmac_f32_e32 v53, v54, v54
	v_add_f32_e32 v52, v53, v52
	v_mul_f32_e32 v53, v61, v61
	v_fmac_f32_e32 v53, v60, v60
	v_add_f32_e32 v52, v53, v52
	v_add_f32_e32 v1, v1, v52
	v_cvt_pk_bf16_f32 v52, v56, v57
	v_cvt_pk_bf16_f32 v53, v58, v59
	v_cvt_pk_bf16_f32 v54, v54, v55
	v_cvt_pk_bf16_f32 v55, v60, v61
	global_store_dwordx4 v[70:71], v[52:55], off offset:256
	s_nop 1
	v_mov_b32_e32 v52, v1
	s_nop 1
	v_permlane16_swap_b32_e32 v52, v1
	s_waitcnt lgkmcnt(0)
	v_add_f32_e32 v52, v1, v52
	v_mov_b32_e32 v53, v52
	s_nop 1
	v_permlane32_swap_b32_e32 v53, v52
	s_and_saveexec_b64 s[0:1], s[38:39]
	s_cbranch_execz .LBB0_1637
	v_lshl_add_u64 v[54:55], v[68:69], 2, s[42:43]
	s_waitcnt lgkmcnt(0)
	v_add_f32_e32 v1, v52, v53
	global_atomic_add_f32 v[54:55], v1, off
; __device__ __forceinline__ unsigned pkbf(float lo, float hi) { f32x2v v = {lo, hi}; bf16x2v b = __builtin_convertvector(v, bf16x2v); return __builtin_bit_cast(unsigned, b); }
;     __device__ __forceinline__ void operator()(const f32x4 (&acc)[2][2][4][2], const Unit& u, int wr, int wc, int fr, int fq) const {
;     ...
;                 const int r = row0 + ai * HALF + m * 16;
;                 bf16_t* xp = XB + (size_t)r * 4096 + col0; float sq = 0.f;
;                 const u32x4 o0 = *(const u32x4*)xp, o1 = *(const u32x4*)(xp + HALF);
; #pragma unroll
;                 for (int bj = 0; bj < 2; ++bj) {
;                     const u32x4 o = bj ? o1 : o0;
;                     f32x4 a = {__uint_as_float(o.x << 16), __uint_as_float(o.x & 0xffff0000u), __uint_as_float(o.y << 16), __uint_as_float(o.y & 0xffff0000u)};
;                     f32x4 b = {__uint_as_float(o.z << 16), __uint_as_float(o.z & 0xffff0000u), __uint_as_float(o.w << 16), __uint_as_float(o.w & 0xffff0000u)};
;                     a += acc[ai][bj][m][0]; b += acc[ai][bj][m][1];
;                     if (Y) { float* yp = Y + (size_t)r * 4096 + col0 + bj * HALF; *(f32x4*)yp = a; *(f32x4*)(yp + 4) = b; }
;                     else {
;                         sq += (a[0] * a[0] + a[1] * a[1]) + (a[2] * a[2] + a[3] * a[3]) + (b[0] * b[0] + b[1] * b[1]) + (b[2] * b[2] + b[3] * b[3]);
;                         u32x4 w; w.x = pkbf(a[0], a[1]); w.y = pkbf(a[2], a[3]); w.z = pkbf(b[0], b[1]); w.w = pkbf(b[2], b[3]);
;                         *(u32x4*)(xp + bj * HALF) = w; } }
;                 if (!Y) { sq += __shfl_xor(sq, 16); sq += __shfl_xor(sq, 32); if (fq == 0) unsafeAtomicAdd(ssq + r, sq); }
.LBB0_1637:
	s_or_b64 exec, exec, s[0:1]
	v_add_u32_e32 v52, 0x90, v144
	s_waitcnt lgkmcnt(0)
	v_ashrrev_i32_e32 v53, 31, v52
	v_lshlrev_b64 v[54:55], 13, v[52:53]
	v_lshl_add_u64 v[54:55], s[36:37], 0, v[54:55]
	v_lshl_add_u64 v[54:55], v[142:143], 1, v[54:55]
	s_waitcnt vmcnt(19)
	v_lshlrev_b32_e32 v64, 16, v196
	v_and_b32_e32 v65, 0xffff0000, v196
	v_lshlrev_b32_e32 v56, 16, v197
	v_and_b32_e32 v57, 0xffff0000, v197
	v_lshlrev_b32_e32 v66, 16, v198
	v_and_b32_e32 v67, 0xffff0000, v198
	v_lshlrev_b32_e32 v58, 16, v199
	v_and_b32_e32 v59, 0xffff0000, v199
	v_pk_add_f32 v[50:51], v[50:51], v[56:57]
	v_pk_add_f32 v[48:49], v[48:49], v[64:65]
	v_pk_add_f32 v[56:57], v[46:47], v[58:59]
	v_pk_add_f32 v[46:47], v[44:45], v[66:67]
	v_mul_f32_e32 v1, v49, v49
	v_mul_f32_e32 v44, v51, v51
	v_fmac_f32_e32 v1, v48, v48
	v_fmac_f32_e32 v44, v50, v50
	v_add_f32_e32 v1, v1, v44
	v_mul_f32_e32 v44, v47, v47
	v_fmac_f32_e32 v44, v46, v46
	v_add_f32_e32 v1, v44, v1
	v_mul_f32_e32 v44, v57, v57
	v_fmac_f32_e32 v44, v56, v56
	v_add_f32_e32 v1, v44, v1
	v_cvt_pk_bf16_f32 v44, v48, v49
	v_cvt_pk_bf16_f32 v45, v50, v51
	v_cvt_pk_bf16_f32 v46, v46, v47
	v_cvt_pk_bf16_f32 v47, v56, v57
	global_store_dwordx4 v[54:55], v[44:47], off
	v_lshlrev_b32_e32 v48, 16, v202
	v_and_b32_e32 v49, 0xffff0000, v202
	v_lshlrev_b32_e32 v44, 16, v200
	v_and_b32_e32 v45, 0xffff0000, v200
	v_lshlrev_b32_e32 v46, 16, v201
	v_and_b32_e32 v47, 0xffff0000, v201
	v_lshlrev_b32_e32 v50, 16, v203
	v_and_b32_e32 v51, 0xffff0000, v203
	v_pk_add_f32 v[42:43], v[42:43], v[46:47]
	v_pk_add_f32 v[40:41], v[40:41], v[44:45]
	v_pk_add_f32 v[44:45], v[38:39], v[50:51]
	v_pk_add_f32 v[38:39], v[36:37], v[48:49]
	v_mul_f32_e32 v36, v41, v41
	v_mul_f32_e32 v37, v43, v43
	v_fmac_f32_e32 v36, v40, v40
	v_fmac_f32_e32 v37, v42, v42
	v_add_f32_e32 v36, v36, v37
	v_mul_f32_e32 v37, v39, v39
	v_fmac_f32_e32 v37, v38, v38
	v_add_f32_e32 v36, v37, v36
	v_mul_f32_e32 v37, v45, v45
	v_fmac_f32_e32 v37, v44, v44
	v_add_f32_e32 v36, v37, v36
	v_add_f32_e32 v1, v1, v36
	v_cvt_pk_bf16_f32 v36, v40, v41
	v_cvt_pk_bf16_f32 v37, v42, v43
	v_cvt_pk_bf16_f32 v38, v38, v39
	v_cvt_pk_bf16_f32 v39, v44, v45
	global_store_dwordx4 v[54:55], v[36:39], off offset:256
	s_nop 1
	v_mov_b32_e32 v36, v1
	s_nop 1
	v_permlane16_swap_b32_e32 v36, v1
	s_waitcnt lgkmcnt(0)
	v_add_f32_e32 v36, v1, v36
	v_mov_b32_e32 v37, v36
	s_nop 1
	v_permlane32_swap_b32_e32 v37, v36
	s_and_saveexec_b64 s[0:1], s[38:39]
	s_cbranch_execz .LBB0_1639
	v_lshl_add_u64 v[38:39], v[52:53], 2, s[42:43]
	s_waitcnt lgkmcnt(0)
	v_add_f32_e32 v1, v36, v37
	global_atomic_add_f32 v[38:39], v1, off
.LBB0_1639:
	s_or_b64 exec, exec, s[0:1]
	v_add_u32_e32 v36, 0xa0, v144
	s_waitcnt lgkmcnt(0)
	v_ashrrev_i32_e32 v37, 31, v36
	v_lshlrev_b64 v[38:39], 13, v[36:37]
	v_lshl_add_u64 v[38:39], s[36:37], 0, v[38:39]
	v_lshl_add_u64 v[38:39], v[142:143], 1, v[38:39]
	s_waitcnt vmcnt(14)
	v_lshlrev_b32_e32 v48, 16, v164
	v_and_b32_e32 v49, 0xffff0000, v164
	v_lshlrev_b32_e32 v40, 16, v165
	v_and_b32_e32 v41, 0xffff0000, v165
	v_lshlrev_b32_e32 v50, 16, v166
	v_and_b32_e32 v51, 0xffff0000, v166
	v_lshlrev_b32_e32 v42, 16, v167
	v_and_b32_e32 v43, 0xffff0000, v167
	v_pk_add_f32 v[34:35], v[34:35], v[40:41]
	v_pk_add_f32 v[32:33], v[32:33], v[48:49]
	v_pk_add_f32 v[40:41], v[30:31], v[42:43]
	v_pk_add_f32 v[30:31], v[28:29], v[50:51]
	v_mul_f32_e32 v1, v33, v33
	v_mul_f32_e32 v28, v35, v35
	v_fmac_f32_e32 v1, v32, v32
	v_fmac_f32_e32 v28, v34, v34
	v_add_f32_e32 v1, v1, v28
	v_mul_f32_e32 v28, v31, v31
	v_fmac_f32_e32 v28, v30, v30
	v_add_f32_e32 v1, v28, v1
	v_mul_f32_e32 v28, v41, v41
	v_fmac_f32_e32 v28, v40, v40
	v_add_f32_e32 v1, v28, v1
	v_cvt_pk_bf16_f32 v28, v32, v33
	v_cvt_pk_bf16_f32 v29, v34, v35
	v_cvt_pk_bf16_f32 v30, v30, v31
	v_cvt_pk_bf16_f32 v31, v40, v41
	global_store_dwordx4 v[38:39], v[28:31], off
	v_lshlrev_b32_e32 v32, 16, v170
	v_and_b32_e32 v33, 0xffff0000, v170
	v_lshlrev_b32_e32 v28, 16, v168
	v_and_b32_e32 v29, 0xffff0000, v168
	v_lshlrev_b32_e32 v30, 16, v169
	v_and_b32_e32 v31, 0xffff0000, v169
	v_lshlrev_b32_e32 v34, 16, v171
	v_and_b32_e32 v35, 0xffff0000, v171
	v_pk_add_f32 v[26:27], v[26:27], v[30:31]
	v_pk_add_f32 v[24:25], v[24:25], v[28:29]
	v_pk_add_f32 v[28:29], v[22:23], v[34:35]
	v_pk_add_f32 v[22:23], v[20:21], v[32:33]
	v_mul_f32_e32 v20, v25, v25
	v_mul_f32_e32 v21, v27, v27
	v_fmac_f32_e32 v20, v24, v24
	v_fmac_f32_e32 v21, v26, v26
	v_add_f32_e32 v20, v20, v21
	v_mul_f32_e32 v21, v23, v23
	v_fmac_f32_e32 v21, v22, v22
	v_add_f32_e32 v20, v21, v20
	v_mul_f32_e32 v21, v29, v29
	v_fmac_f32_e32 v21, v28, v28
	v_add_f32_e32 v20, v21, v20
	v_add_f32_e32 v1, v1, v20
	v_cvt_pk_bf16_f32 v20, v24, v25
	v_cvt_pk_bf16_f32 v21, v26, v27
	v_cvt_pk_bf16_f32 v22, v22, v23
	v_cvt_pk_bf16_f32 v23, v28, v29
	global_store_dwordx4 v[38:39], v[20:23], off offset:256
	s_nop 1
	v_mov_b32_e32 v20, v1
	s_nop 1
	v_permlane16_swap_b32_e32 v20, v1
	s_waitcnt lgkmcnt(0)
	v_add_f32_e32 v20, v1, v20
	v_mov_b32_e32 v21, v20
	s_nop 1
	v_permlane32_swap_b32_e32 v21, v20
	s_and_saveexec_b64 s[0:1], s[38:39]
	s_cbranch_execz .LBB0_1641
	v_lshl_add_u64 v[22:23], v[36:37], 2, s[42:43]
	s_waitcnt lgkmcnt(0)
	v_add_f32_e32 v1, v20, v21
	global_atomic_add_f32 v[22:23], v1, off
